# P1->GEMM1 seam XCD-local too: co-location census (one 64-bit atomic per WG) resolved at P1 entry, P1 rows remapped to the consuming XCD, phase-0 data published with an early writeback + counter
# baseline (speedup 1.0000x reference)
; #define LAS __attribute__((address_space(3)))
; __device__ __forceinline__ unsigned xb_add(unsigned* p, unsigned v) { return __hip_atomic_fetch_add(p, v, __ATOMIC_RELAXED, __HIP_MEMORY_SCOPE_AGENT); }
; __device__ __forceinline__ unsigned xb_xcc_id() { return (unsigned)__builtin_amdgcn_s_getreg((3 << 11) | 20) & 0xFu; }
; __device__ __forceinline__ XcdBarrier xcd_barrier_post(unsigned* bar, volatile LAS unsigned* st) {
;     XcdBarrier b; b.bar = bar; b.x = xb_xcc_id(); b.st = st;
;     if (threadIdx.x == 0) (void)xb_add(&bar[XB_XCNT(b.x)], 1u);
;     return b;
; }
.LBB0_2:
	s_load_dwordx2 s[92:93], s[0:1], 0x90
	s_load_dwordx4 s[88:91], s[0:1], 0x80
	v_and_b32_e32 v200, 0x3ff, v0
	v_cmp_gt_u32_e32 vcc, 2, v200
	s_and_saveexec_b64 s[2:3], vcc
	v_lshl_add_u32 v1, v200, 2, 0
	v_add_u32_e32 v1, 0x24040, v1
	v_mov_b32_e32 v2, 0
	ds_write_b32 v1, v2
	s_or_b64 exec, exec, s[2:3]
	s_waitcnt lgkmcnt(0)
	s_add_u32 s2, s90, 0x70000
	s_addc_u32 s3, s91, 0
	v_writelane_b32 v254, s2, 2
	s_barrier
	s_nop 0
	v_writelane_b32 v254, s3, 3
	s_getreg_b32 s2, hwreg(HW_REG_XCC_ID, 0, 4)
	s_and_b32 s2, s2, 15
	v_writelane_b32 v254, s2, 4
	v_cmp_eq_u32_e64 s[4:5], 0, v200
	s_mov_b64 s[2:3], exec
	s_nop 0
	v_writelane_b32 v254, s4, 5
	s_nop 1
	v_writelane_b32 v254, s5, 6
	s_and_b64 s[4:5], s[2:3], s[4:5]
	s_mov_b64 exec, s[4:5]
	s_cbranch_execz .LBB0_7
	s_mov_b64 s[4:5], exec
	v_mbcnt_lo_u32_b32 v1, s4, 0
	v_mbcnt_hi_u32_b32 v1, s5, v1
	v_cmp_eq_u32_e32 vcc, 0, v1
	s_and_b64 s[6:7], exec, vcc
	s_mov_b64 exec, s[6:7]
	s_cbranch_execz .LBB0_7
	v_readlane_b32 s6, v254, 4
	s_bcnt1_i32_b64 s4, s[4:5]
	s_lshl_b32 s6, s6, 8
	v_mov_b32_e32 v2, s4
	v_readlane_b32 s4, v254, 2
	v_mov_b32_e32 v1, s6
	v_readlane_b32 s5, v254, 3
	s_nop 4
	global_atomic_add v1, v2, s[4:5] offset:1024
	s_lshr_b32 s6, s6, 8
	s_lshl_b32 s6, s6, 3
	s_lshl_b64 s[6:7], 1, s6
	v_mov_b32_e32 v4, s6
	v_mov_b32_e32 v5, s7
	s_and_b32 s6, s80, 7
	s_lshl_b32 s6, s6, 3
	s_add_i32 s6, s6, 0x3840
	v_mov_b32_e32 v3, s6
	global_atomic_add_x2 v3, v[4:5], s[4:5]

; __device__ __forceinline__ void phase1(const Ptrs& P, int G) {
;     const int tid = threadIdx.x, lane = tid & 63, wave = tid >> 6;
;     const int gw = blockIdx.x * 8 + wave, NGW = G * 8;
;     const float* mod = (const float*)(P.ws + WS_MOD); bf16_t* H = (bf16_t*)(P.ws + WS_H);
;     if (tid == 0) {
;         unsigned* cnt = (unsigned*)(P.ws + WS_BAR) + 3520; const unsigned want = G < 96 ? (unsigned)G : 96u; unsigned sp = 0;
;         while (__hip_atomic_load(cnt, __ATOMIC_RELAXED, __HIP_MEMORY_SCOPE_AGENT) < want) { __builtin_amdgcn_s_sleep(2); if (++sp > (1u << 22)) break; }
;         __builtin_amdgcn_fence(__ATOMIC_ACQUIRE, "agent"); asm volatile("s_waitcnt vmcnt(0)" ::: "memory");
;     }
;     __syncthreads();
.LBB0_266:
	s_cmp_lt_i32 s92, 2
	s_cselect_b64 s[0:1], -1, 0
	s_cmp_gt_i32 s93, 1
	s_cselect_b64 s[2:3], -1, 0
	s_and_b64 s[2:3], s[0:1], s[2:3]
	s_andn2_b64 vcc, exec, s[2:3]
	s_cbranch_vccnz .LBB0_285
	s_waitcnt vmcnt(0)
	s_barrier
	s_mov_b64 s[0:1], exec
	v_readlane_b32 s4, v254, 5
	v_readlane_b32 s5, v254, 6
	s_and_b64 s[4:5], s[0:1], s[4:5]
	s_mov_b64 exec, s[4:5]
	s_cbranch_execz .LBB0_277
	v_mov_b32_e32 v0, 0x73840
	v_mov_b32_e32 v19, 0
.Lcen_spin:
	global_load_dwordx4 v[2:5], v0, s[90:91] sc1
	global_load_dwordx4 v[6:9], v0, s[90:91] offset:16 sc1
	global_load_dwordx4 v[10:13], v0, s[90:91] offset:32 sc1
	global_load_dwordx4 v[14:17], v0, s[90:91] offset:48 sc1
	v_add_u32_e32 v19, 1, v19
	s_waitcnt vmcnt(0)
	v_sad_u8 v18, v2, 0, 0
	v_sad_u8 v18, v3, 0, v18
	v_sad_u8 v18, v4, 0, v18
	v_sad_u8 v18, v5, 0, v18
	v_sad_u8 v18, v6, 0, v18
	v_sad_u8 v18, v7, 0, v18
	v_sad_u8 v18, v8, 0, v18
	v_sad_u8 v18, v9, 0, v18
	v_sad_u8 v18, v10, 0, v18
	v_sad_u8 v18, v11, 0, v18
	v_sad_u8 v18, v12, 0, v18
	v_sad_u8 v18, v13, 0, v18
	v_sad_u8 v18, v14, 0, v18
	v_sad_u8 v18, v15, 0, v18
	v_sad_u8 v18, v16, 0, v18
	v_sad_u8 v18, v17, 0, v18
	v_cmp_eq_u32_e32 vcc, 0x100, v18
	s_cbranch_vccnz .Lcen_ok
	v_cmp_gt_u32_e32 vcc, 0x4000, v19
	s_cbranch_vccz .Lcen_bad
	s_sleep 2
	s_branch .Lcen_spin
.Lcen_bad:
	s_mov_b32 s98, 1
	s_branch .Lcen_done
.Lcen_ok:
	v_or3_b32 v18, v2, v4, v6
	v_or3_b32 v18, v18, v8, v10
	v_or3_b32 v18, v18, v12, v14
	v_or_b32_e32 v18, v18, v16
	v_or3_b32 v19, v3, v5, v7
	v_or3_b32 v19, v19, v9, v11
	v_or3_b32 v19, v19, v13, v15
	v_or_b32_e32 v19, v19, v17
	s_mov_b32 s6, 0x20202020
	v_cmp_ne_u32_e32 vcc, s6, v18
	v_cmp_ne_u32_e64 s[8:9], s6, v19
	s_or_b64 vcc, vcc, s[8:9]
	s_cmp_lg_u64 vcc, 0
	s_cselect_b32 s98, 1, 0
.Lcen_done:
	v_mov_b32_e32 v2, 0x24054
	v_mov_b32_e32 v3, s98
	ds_write_b32 v2, v3
	s_cmp_lg_u32 s98, 0
	s_cbranch_scc1 .Lcen_nopub
	buffer_wbl2 sc1
	s_waitcnt vmcnt(0)
	v_mov_b32_e32 v2, 0x73928
	v_mov_b32_e32 v3, 1
	global_atomic_add v2, v3, s[90:91]
.Lcen_nopub:
	s_add_u32 s4, s90, 0x73700
	s_addc_u32 s5, s91, 0
	s_min_i32 s8, s83, 0x60
	s_mov_b32 s9, 0x400001
	v_mov_b32_e32 v0, 0
	s_branch .LBB0_270

; __device__ __forceinline__ void phase1(const Ptrs& P, int G) {
;     ...
;     __syncthreads();
;     f32x4 g[2][2];
; #pragma unroll
;     for (int j = 0; j < 2; ++j) { g[j][0] = *(const f32x4*)(P.g_pre + 512 * j + 8 * lane); g[j][1] = *(const f32x4*)(P.g_pre + 512 * j + 8 * lane + 4); }
;     for (int row0 = gw; row0 < T; row0 += 2 * NGW) {
;         f32x4 v[2][2][2];
; #pragma unroll
;         for (int r = 0; r < 2; ++r) { const int row = row0 + r * NGW; if (row < T) { const float* xr = P.x + (size_t)row * DM + 8 * lane;
; #pragma unroll
;             for (int j = 0; j < 2; ++j) { v[r][j][0] = __builtin_nontemporal_load((const f32x4*)(xr + 512 * j)); v[r][j][1] = __builtin_nontemporal_load((const f32x4*)(xr + 512 * j + 4)); } } }
; #pragma unroll
.LBB0_277:
	s_or_b64 exec, exec, s[0:1]
	v_lshrrev_b32_e32 v0, 6, v200
	v_lshl_add_u32 v58, s80, 3, v0
	s_mov_b32 s12, 0x8000
	s_waitcnt lgkmcnt(0)
	s_barrier
	v_mov_b32_e32 v1, 0x24054
	ds_read_b32 v1, v1
	s_waitcnt lgkmcnt(0)
	v_readfirstlane_b32 s98, v1
	s_cmp_lg_u32 s98, 0
	s_cbranch_scc1 .Lp1_glob
	s_and_b32 s12, s80, 7
	s_lshl_b32 s12, s12, 12
	s_andn2_b32 s13, s80, 7
	s_add_i32 s13, s13, s12
	v_add_u32_e32 v58, s13, v0
	s_add_i32 s12, s12, 0x1000
.Lp1_glob:
	v_cmp_gt_i32_e32 vcc, s12, v58
	s_and_saveexec_b64 s[0:1], vcc
	s_cbranch_execz .LBB0_284
	v_lshlrev_b32_e32 v0, 3, v200
	v_and_b32_e32 v16, 0x1f8, v0
	v_lshlrev_b32_e32 v48, 2, v16
	global_load_dwordx4 v[0:3], v48, s[58:59] offset:16
	global_load_dwordx4 v[4:7], v48, s[58:59]
	global_load_dwordx4 v[8:11], v48, s[58:59] offset:2064
	global_load_dwordx4 v[12:15], v48, s[58:59] offset:2048
	v_mbcnt_lo_u32_b32 v17, -1, 0
	v_mbcnt_hi_u32_b32 v17, -1, v17
	v_and_b32_e32 v18, 64, v17
	v_add_u32_e32 v18, 64, v18
	v_xor_b32_e32 v19, 1, v17
	v_cmp_lt_i32_e32 vcc, v19, v18
	v_mov_b32_e32 v49, 0
	s_lshl_b32 s13, s83, 3
	s_cmp_eq_u32 s98, 0
	s_cselect_b32 s13, 0x100, s13
	v_cndmask_b32_e32 v19, v17, v19, vcc
	v_lshlrev_b32_e32 v60, 2, v19
	v_xor_b32_e32 v19, 2, v17
	v_cmp_lt_i32_e32 vcc, v19, v18
	v_lshl_add_u64 v[50:51], s[48:49], 0, v[48:49]
	v_lshlrev_b32_e32 v48, 1, v16
	v_cndmask_b32_e32 v19, v17, v19, vcc
	v_lshlrev_b32_e32 v61, 2, v19
	v_xor_b32_e32 v19, 4, v17
	v_cmp_lt_i32_e32 vcc, v19, v18
	s_add_u32 s4, s90, 0x80000
	v_lshl_add_u64 v[20:21], s[90:91], 0, v[48:49]
	v_cndmask_b32_e32 v19, v17, v19, vcc
	v_lshlrev_b32_e32 v62, 2, v19
	v_xor_b32_e32 v19, 8, v17
	v_cmp_lt_i32_e32 vcc, v19, v18
	s_mov_b64 s[6:7], 0x15000000
	s_addc_u32 s5, s91, 0
	v_cndmask_b32_e32 v19, v17, v19, vcc
	v_lshlrev_b32_e32 v63, 2, v19
	v_xor_b32_e32 v19, 16, v17
	v_cmp_lt_i32_e32 vcc, v19, v18
	v_lshl_add_u64 v[52:53], v[20:21], 0, s[6:7]
	s_mov_b64 s[6:7], 0
	v_cndmask_b32_e32 v19, v17, v19, vcc
	v_lshlrev_b32_e32 v64, 2, v19
	v_xor_b32_e32 v19, 32, v17
	v_cmp_lt_i32_e32 vcc, v19, v18
	v_or_b32_e32 v18, 0x200, v16
	v_mov_b32_e32 v66, 0x358637bd
	v_cndmask_b32_e32 v17, v17, v19, vcc
	v_lshlrev_b32_e32 v65, 2, v17
	s_mov_b64 s[8:9], 0x1000
	v_lshlrev_b32_e32 v48, 2, v16
	v_lshlrev_b32_e32 v54, 2, v18
	s_add_i32 s14, s12, -1
	s_branch .LBB0_280

; __device__ __forceinline__ unsigned xb_ld(unsigned* p)              { return __hip_atomic_load(p, __ATOMIC_RELAXED, __HIP_MEMORY_SCOPE_AGENT); }
; __device__ __forceinline__ unsigned xb_add(unsigned* p, unsigned v) { return __hip_atomic_fetch_add(p, v, __ATOMIC_RELAXED, __HIP_MEMORY_SCOPE_AGENT); }
; #define XB_SPIN(cond, bar) do { unsigned _sp = 0; while (cond) { __builtin_amdgcn_s_sleep(1); \
;     if ((++_sp & 255u) == 0u) { if (xb_ld(&(bar)[XB_TMO])) break; if (_sp > XB_SPIN_CAP) { atomicAdd(&(bar)[XB_TMO], 1u); break; } } } } while (0)
; __device__ __forceinline__ void xcd_barrier(const XcdBarrier& b) {
;     asm volatile("s_waitcnt vmcnt(0)" ::: "memory");
;     __syncthreads();
;     if (threadIdx.x == 0) {
;         unsigned* bar = b.bar;
;         __builtin_amdgcn_s_waitcnt(0);
;         unsigned nloc = b.st[0], nx = b.st[1];
;         if (nloc == 0u) { xcd_barrier_complete(bar, b.x, nloc, nx); b.st[0] = nloc; b.st[1] = nx; }
;         const unsigned old = xb_add(&bar[XB_XSUB(b.x)], 1u);
;         const unsigned gen = old / nloc;
;         if (old + 1u == (gen + 1u) * nloc) {
;             __builtin_amdgcn_fence(__ATOMIC_RELEASE, "agent");
;             asm volatile("s_waitcnt vmcnt(0)" ::: "memory");
;             const unsigned og = xb_add(&bar[XB_TOP], 1u);
;             const unsigned tg = og / nx;
;             if (og + 1u == (tg + 1u) * nx) xb_add(&bar[XB_TOPGEN], 1u);
;             else XB_SPIN(xb_ld(&bar[XB_TOPGEN]) == tg, bar);
.LBB0_285:
	s_cmp_gt_i32 s93, 2
	s_cselect_b64 s[0:1], -1, 0
	s_and_b64 s[2:3], s[2:3], s[0:1]
	s_andn2_b64 vcc, exec, s[2:3]
	s_cbranch_vccnz .LBB0_339
	s_waitcnt vmcnt(0)
	s_barrier
	s_mov_b64 s[2:3], exec
	v_readlane_b32 s4, v254, 5
	v_readlane_b32 s5, v254, 6
	s_and_b64 s[4:5], s[2:3], s[4:5]
	s_mov_b64 exec, s[4:5]
	s_cbranch_execz .LBB0_338
	s_cmp_lg_u32 s98, 0
	s_cbranch_scc1 .Lfb_orig_1
	v_readlane_b32 s4, v254, 4
	v_readlane_b32 s6, v254, 2
	v_readlane_b32 s7, v254, 3
	s_lshl_b32 s4, s4, 8
	s_add_u32 s4, s6, s4
	s_addc_u32 s5, s7, 0
	v_mov_b32_e32 v0, 0
	v_mov_b32_e32 v1, 1
	v_mov_b32_e32 v2, 0
	v_mov_b32_e32 v3, 0x73928
	global_atomic_add v1, v0, v1, s[4:5] offset:1088 sc0
	global_load_dword v4, v3, s[90:91] sc1
	s_waitcnt vmcnt(0)
	v_cmp_le_u32_e32 vcc, 31, v1
	s_cbranch_vccnz .Lfb_md_1

; __device__ __forceinline__ unsigned xb_ld(unsigned* p)              { return __hip_atomic_load(p, __ATOMIC_RELAXED, __HIP_MEMORY_SCOPE_AGENT); }
; #define XB_SPIN(cond, bar) do { unsigned _sp = 0; while (cond) { __builtin_amdgcn_s_sleep(1); \
;     if ((++_sp & 255u) == 0u) { if (xb_ld(&(bar)[XB_TMO])) break; if (_sp > XB_SPIN_CAP) { atomicAdd(&(bar)[XB_TMO], 1u); break; } } } } while (0)
; __device__ __forceinline__ void xcd_barrier(const XcdBarrier& b) {
;     ...
;             asm volatile("s_waitcnt vmcnt(0)" ::: "memory");
;         } else {
;             XB_SPIN(xb_ld(&bar[XB_XGEN(b.x)]) == gen, bar);
;             __builtin_amdgcn_fence(__ATOMIC_ACQUIRE, "agent");
;             asm volatile("s_waitcnt vmcnt(0)" ::: "memory");
.Lfb_md_1:
	v_cmp_le_u32_e32 vcc, 0x100, v4
	s_cbranch_vccnz .Lfb_done_1
	global_load_dword v4, v3, s[90:91] sc1
	v_add_u32_e32 v2, 1, v2
	s_waitcnt vmcnt(0)
	v_cmp_gt_u32_e32 vcc, 0x10000, v2
	s_cbranch_vccnz .Lfb_md_1

; __device__ __forceinline__ unsigned xb_ld(unsigned* p)              { return __hip_atomic_load(p, __ATOMIC_RELAXED, __HIP_MEMORY_SCOPE_AGENT); }
; __device__ __forceinline__ unsigned xb_add(unsigned* p, unsigned v) { return __hip_atomic_fetch_add(p, v, __ATOMIC_RELAXED, __HIP_MEMORY_SCOPE_AGENT); }
; #define XB_SPIN(cond, bar) do { unsigned _sp = 0; while (cond) { __builtin_amdgcn_s_sleep(1); \
;     if ((++_sp & 255u) == 0u) { if (xb_ld(&(bar)[XB_TMO])) break; if (_sp > XB_SPIN_CAP) { atomicAdd(&(bar)[XB_TMO], 1u); break; } } } } while (0)
; __device__ __forceinline__ void xcd_barrier(const XcdBarrier& b) {
;     asm volatile("s_waitcnt vmcnt(0)" ::: "memory");
;     __syncthreads();
;     if (threadIdx.x == 0) {
;         unsigned* bar = b.bar;
;         __builtin_amdgcn_s_waitcnt(0);
;         unsigned nloc = b.st[0], nx = b.st[1];
;         if (nloc == 0u) { xcd_barrier_complete(bar, b.x, nloc, nx); b.st[0] = nloc; b.st[1] = nx; }
;         const unsigned old = xb_add(&bar[XB_XSUB(b.x)], 1u);
;         const unsigned gen = old / nloc;
;         if (old + 1u == (gen + 1u) * nloc) {
;             __builtin_amdgcn_fence(__ATOMIC_RELEASE, "agent");
;             asm volatile("s_waitcnt vmcnt(0)" ::: "memory");
;             const unsigned og = xb_add(&bar[XB_TOP], 1u);
;             const unsigned tg = og / nx;
;             if (og + 1u == (tg + 1u) * nx) xb_add(&bar[XB_TOPGEN], 1u);
;             else XB_SPIN(xb_ld(&bar[XB_TOPGEN]) == tg, bar);
.LBB0_635:
	s_waitcnt vmcnt(0)
	s_waitcnt vmcnt(0) lgkmcnt(0)
	s_barrier
	s_mov_b64 s[0:1], exec
	v_readlane_b32 s2, v254, 5
	v_readlane_b32 s3, v254, 6
	s_and_b64 s[2:3], s[0:1], s[2:3]
	s_mov_b64 exec, s[2:3]
	s_cbranch_execz .LBB0_687
	s_cmp_lg_u32 s98, 0
	s_cbranch_scc1 .Lfb_orig_2
	v_readlane_b32 s4, v254, 4
	v_readlane_b32 s6, v254, 2
	v_readlane_b32 s7, v254, 3
	s_lshl_b32 s4, s4, 8
	s_add_u32 s4, s6, s4
	s_addc_u32 s5, s7, 0
	v_mov_b32_e32 v0, 0
	v_mov_b32_e32 v1, 1
	v_mov_b32_e32 v2, 0
	global_atomic_add v1, v0, v1, s[4:5] offset:1088 sc0
	s_waitcnt vmcnt(0)
	v_cmp_le_u32_e32 vcc, 63, v1
	s_cbranch_vccnz .Lfb_done_2

; __device__ __forceinline__ unsigned xb_ld(unsigned* p)              { return __hip_atomic_load(p, __ATOMIC_RELAXED, __HIP_MEMORY_SCOPE_AGENT); }
; __device__ __forceinline__ unsigned xb_add(unsigned* p, unsigned v) { return __hip_atomic_fetch_add(p, v, __ATOMIC_RELAXED, __HIP_MEMORY_SCOPE_AGENT); }
; #define XB_SPIN(cond, bar) do { unsigned _sp = 0; while (cond) { __builtin_amdgcn_s_sleep(1); \
;     if ((++_sp & 255u) == 0u) { if (xb_ld(&(bar)[XB_TMO])) break; if (_sp > XB_SPIN_CAP) { atomicAdd(&(bar)[XB_TMO], 1u); break; } } } } while (0)
; __device__ __forceinline__ void xcd_barrier(const XcdBarrier& b) {
;     asm volatile("s_waitcnt vmcnt(0)" ::: "memory");
;     __syncthreads();
;     if (threadIdx.x == 0) {
;         unsigned* bar = b.bar;
;         __builtin_amdgcn_s_waitcnt(0);
;         unsigned nloc = b.st[0], nx = b.st[1];
;         if (nloc == 0u) { xcd_barrier_complete(bar, b.x, nloc, nx); b.st[0] = nloc; b.st[1] = nx; }
;         const unsigned old = xb_add(&bar[XB_XSUB(b.x)], 1u);
;         const unsigned gen = old / nloc;
;         if (old + 1u == (gen + 1u) * nloc) {
;             __builtin_amdgcn_fence(__ATOMIC_RELEASE, "agent");
;             asm volatile("s_waitcnt vmcnt(0)" ::: "memory");
;             const unsigned og = xb_add(&bar[XB_TOP], 1u);
;             const unsigned tg = og / nx;
;             if (og + 1u == (tg + 1u) * nx) xb_add(&bar[XB_TOPGEN], 1u);
;             else XB_SPIN(xb_ld(&bar[XB_TOPGEN]) == tg, bar);
.LBB0_1057:
	s_cmp_lt_i32 s92, 4
	s_cselect_b64 s[2:3], -1, 0
	s_cmp_gt_i32 s93, 4
	s_cselect_b64 s[0:1], -1, 0
	s_and_b64 s[2:3], s[2:3], s[0:1]
	s_andn2_b64 vcc, exec, s[2:3]
	s_cbranch_vccnz .LBB0_1111
	s_waitcnt vmcnt(0)
	s_waitcnt lgkmcnt(0)
	s_barrier
	s_mov_b64 s[2:3], exec
	v_readlane_b32 s4, v254, 5
	v_readlane_b32 s5, v254, 6
	s_and_b64 s[4:5], s[2:3], s[4:5]
	s_mov_b64 exec, s[4:5]
	s_cbranch_execz .LBB0_1110
	s_cmp_lg_u32 s98, 0
	s_cbranch_scc1 .Lfb_orig_4
	v_readlane_b32 s4, v254, 4
	v_readlane_b32 s6, v254, 2
	v_readlane_b32 s7, v254, 3
	s_lshl_b32 s4, s4, 8
	s_add_u32 s4, s6, s4
	s_addc_u32 s5, s7, 0
	v_mov_b32_e32 v0, 0
	v_mov_b32_e32 v1, 1
	v_mov_b32_e32 v2, 0
	global_atomic_add v1, v0, v1, s[4:5] offset:1088 sc0
	s_waitcnt vmcnt(0)
	v_cmp_le_u32_e32 vcc, 95, v1
	s_cbranch_vccnz .Lfb_done_4

; __device__ __forceinline__ unsigned xb_ld(unsigned* p)              { return __hip_atomic_load(p, __ATOMIC_RELAXED, __HIP_MEMORY_SCOPE_AGENT); }
; __device__ __forceinline__ unsigned xb_add(unsigned* p, unsigned v) { return __hip_atomic_fetch_add(p, v, __ATOMIC_RELAXED, __HIP_MEMORY_SCOPE_AGENT); }
; #define XB_SPIN(cond, bar) do { unsigned _sp = 0; while (cond) { __builtin_amdgcn_s_sleep(1); \
;     if ((++_sp & 255u) == 0u) { if (xb_ld(&(bar)[XB_TMO])) break; if (_sp > XB_SPIN_CAP) { atomicAdd(&(bar)[XB_TMO], 1u); break; } } } } while (0)
; __device__ __forceinline__ void xcd_barrier(const XcdBarrier& b) {
;     asm volatile("s_waitcnt vmcnt(0)" ::: "memory");
;     __syncthreads();
;     if (threadIdx.x == 0) {
;         unsigned* bar = b.bar;
;         __builtin_amdgcn_s_waitcnt(0);
;         unsigned nloc = b.st[0], nx = b.st[1];
;         if (nloc == 0u) { xcd_barrier_complete(bar, b.x, nloc, nx); b.st[0] = nloc; b.st[1] = nx; }
;         const unsigned old = xb_add(&bar[XB_XSUB(b.x)], 1u);
;         const unsigned gen = old / nloc;
;         if (old + 1u == (gen + 1u) * nloc) {
;             __builtin_amdgcn_fence(__ATOMIC_RELEASE, "agent");
;             asm volatile("s_waitcnt vmcnt(0)" ::: "memory");
;             const unsigned og = xb_add(&bar[XB_TOP], 1u);
;             const unsigned tg = og / nx;
;             if (og + 1u == (tg + 1u) * nx) xb_add(&bar[XB_TOPGEN], 1u);
;             else XB_SPIN(xb_ld(&bar[XB_TOPGEN]) == tg, bar);
.LBB0_1234:
	s_cmp_gt_i32 s93, 5
	s_cselect_b64 s[0:1], -1, 0
	s_and_b64 s[2:3], s[2:3], s[0:1]
	s_andn2_b64 vcc, exec, s[2:3]
	s_cbranch_vccnz .LBB0_1288
	s_waitcnt vmcnt(0)
	s_waitcnt lgkmcnt(0)
	s_barrier
	s_mov_b64 s[2:3], exec
	v_readlane_b32 s4, v254, 5
	v_readlane_b32 s5, v254, 6
	s_and_b64 s[4:5], s[2:3], s[4:5]
	s_mov_b64 exec, s[4:5]
	s_cbranch_execz .LBB0_1287
	s_cmp_lg_u32 s98, 0
	s_cbranch_scc1 .Lfb_orig_5
	v_readlane_b32 s4, v254, 4
	v_readlane_b32 s6, v254, 2
	v_readlane_b32 s7, v254, 3
	s_lshl_b32 s4, s4, 8
	s_add_u32 s4, s6, s4
	s_addc_u32 s5, s7, 0
	v_mov_b32_e32 v0, 0
	v_mov_b32_e32 v1, 1
	v_mov_b32_e32 v2, 0
	global_atomic_add v1, v0, v1, s[4:5] offset:1088 sc0
	s_waitcnt vmcnt(0)
	v_cmp_le_u32_e32 vcc, 127, v1
	s_cbranch_vccnz .Lfb_done_5

; __device__ __forceinline__ unsigned xb_ld(unsigned* p)              { return __hip_atomic_load(p, __ATOMIC_RELAXED, __HIP_MEMORY_SCOPE_AGENT); }
; __device__ __forceinline__ unsigned xb_add(unsigned* p, unsigned v) { return __hip_atomic_fetch_add(p, v, __ATOMIC_RELAXED, __HIP_MEMORY_SCOPE_AGENT); }
; #define XB_SPIN(cond, bar) do { unsigned _sp = 0; while (cond) { __builtin_amdgcn_s_sleep(1); \
;     if ((++_sp & 255u) == 0u) { if (xb_ld(&(bar)[XB_TMO])) break; if (_sp > XB_SPIN_CAP) { atomicAdd(&(bar)[XB_TMO], 1u); break; } } } } while (0)
; __device__ __forceinline__ void xcd_barrier(const XcdBarrier& b) {
;     asm volatile("s_waitcnt vmcnt(0)" ::: "memory");
;     __syncthreads();
;     if (threadIdx.x == 0) {
;         unsigned* bar = b.bar;
;         __builtin_amdgcn_s_waitcnt(0);
;         unsigned nloc = b.st[0], nx = b.st[1];
;         if (nloc == 0u) { xcd_barrier_complete(bar, b.x, nloc, nx); b.st[0] = nloc; b.st[1] = nx; }
;         const unsigned old = xb_add(&bar[XB_XSUB(b.x)], 1u);
;         const unsigned gen = old / nloc;
;         if (old + 1u == (gen + 1u) * nloc) {
;             __builtin_amdgcn_fence(__ATOMIC_RELEASE, "agent");
;             asm volatile("s_waitcnt vmcnt(0)" ::: "memory");
;             const unsigned og = xb_add(&bar[XB_TOP], 1u);
;             const unsigned tg = og / nx;
;             if (og + 1u == (tg + 1u) * nx) xb_add(&bar[XB_TOPGEN], 1u);
;             else XB_SPIN(xb_ld(&bar[XB_TOPGEN]) == tg, bar);
.LBB0_1320:
	s_cmp_gt_i32 s93, 6
	s_cselect_b64 s[0:1], -1, 0
	s_and_b64 s[2:3], s[4:5], s[0:1]
	s_andn2_b64 vcc, exec, s[2:3]
	s_cbranch_vccnz .LBB0_1374
	s_waitcnt vmcnt(0)
	s_waitcnt lgkmcnt(0)
	s_barrier
	s_mov_b64 s[2:3], exec
	v_readlane_b32 s4, v254, 5
	v_readlane_b32 s5, v254, 6
	s_and_b64 s[4:5], s[2:3], s[4:5]
	s_mov_b64 exec, s[4:5]
	s_cbranch_execz .LBB0_1373
	s_cmp_lg_u32 s98, 0
	s_cbranch_scc1 .Lfb_orig_6
	v_readlane_b32 s4, v254, 4
	v_readlane_b32 s6, v254, 2
	v_readlane_b32 s7, v254, 3
	s_lshl_b32 s4, s4, 8
	s_add_u32 s4, s6, s4
	s_addc_u32 s5, s7, 0
	v_mov_b32_e32 v0, 0
	v_mov_b32_e32 v1, 1
	v_mov_b32_e32 v2, 0
	global_atomic_add v1, v0, v1, s[4:5] offset:1088 sc0
	s_waitcnt vmcnt(0)
	v_cmp_le_u32_e32 vcc, 159, v1
	s_cbranch_vccz .Lfb_spin_6
	v_mov_b32_e32 v1, 0x73904
	v_mov_b32_e32 v2, 1
	global_atomic_add v1, v2, s[90:91]
	v_mov_b32_e32 v2, 0
	s_branch .Lfb_done_6
.Lfb_spin_6:
	global_load_dword v1, v0, s[4:5] offset:1088 sc1
	v_add_u32_e32 v2, 1, v2
	s_waitcnt vmcnt(0)
	v_cmp_le_u32_e32 vcc, 160, v1
	s_cbranch_vccnz .Lfb_done_6
	v_cmp_gt_u32_e32 vcc, 0x8000, v2
	s_cbranch_vccnz .Lfb_spin_6
.Lfb_done_6:
	buffer_inv sc1
	s_waitcnt vmcnt(0)
	s_branch .LBB0_1373

; __device__ __forceinline__ unsigned xb_ld(unsigned* p)              { return __hip_atomic_load(p, __ATOMIC_RELAXED, __HIP_MEMORY_SCOPE_AGENT); }
; __device__ __forceinline__ unsigned xb_add(unsigned* p, unsigned v) { return __hip_atomic_fetch_add(p, v, __ATOMIC_RELAXED, __HIP_MEMORY_SCOPE_AGENT); }
; #define XB_SPIN(cond, bar) do { unsigned _sp = 0; while (cond) { __builtin_amdgcn_s_sleep(1); \
;     if ((++_sp & 255u) == 0u) { if (xb_ld(&(bar)[XB_TMO])) break; if (_sp > XB_SPIN_CAP) { atomicAdd(&(bar)[XB_TMO], 1u); break; } } } } while (0)
; __device__ __forceinline__ void xcd_barrier(const XcdBarrier& b) {
;     asm volatile("s_waitcnt vmcnt(0)" ::: "memory");
;     __syncthreads();
;     if (threadIdx.x == 0) {
;         unsigned* bar = b.bar;
;         __builtin_amdgcn_s_waitcnt(0);
;         unsigned nloc = b.st[0], nx = b.st[1];
;         if (nloc == 0u) { xcd_barrier_complete(bar, b.x, nloc, nx); b.st[0] = nloc; b.st[1] = nx; }
;         const unsigned old = xb_add(&bar[XB_XSUB(b.x)], 1u);
;         const unsigned gen = old / nloc;
;         if (old + 1u == (gen + 1u) * nloc) {
;             __builtin_amdgcn_fence(__ATOMIC_RELEASE, "agent");
;             asm volatile("s_waitcnt vmcnt(0)" ::: "memory");
;             const unsigned og = xb_add(&bar[XB_TOP], 1u);
;             const unsigned tg = og / nx;
;             if (og + 1u == (tg + 1u) * nx) xb_add(&bar[XB_TOPGEN], 1u);
;             else XB_SPIN(xb_ld(&bar[XB_TOPGEN]) == tg, bar);
;             __builtin_amdgcn_fence(__ATOMIC_ACQUIRE, "agent");
;             xb_add(&bar[XB_XGEN(b.x)], 1u);
;             asm volatile("s_waitcnt vmcnt(0)" ::: "memory");
;         } else {
;             XB_SPIN(xb_ld(&bar[XB_XGEN(b.x)]) == gen, bar);
;             __builtin_amdgcn_fence(__ATOMIC_ACQUIRE, "agent");
;             asm volatile("s_waitcnt vmcnt(0)" ::: "memory");
;         }
.LBB0_1404:
	s_cmp_gt_i32 s93, 7
	s_cselect_b64 s[0:1], -1, 0
	s_and_b64 s[2:3], s[4:5], s[0:1]
	s_andn2_b64 vcc, exec, s[2:3]
	s_cbranch_vccnz .LBB0_1458
	s_waitcnt vmcnt(0)
	s_waitcnt vmcnt(0) lgkmcnt(0)
	s_barrier
	s_mov_b64 s[2:3], exec
	v_readlane_b32 s4, v254, 5
	v_readlane_b32 s5, v254, 6
	s_and_b64 s[4:5], s[2:3], s[4:5]
	s_mov_b64 exec, s[4:5]
	s_cbranch_execz .LBB0_1457
	s_cmp_lg_u32 s98, 0
	s_cbranch_scc1 .Lfb_orig_7
	v_readlane_b32 s4, v254, 4
	v_readlane_b32 s6, v254, 2
	v_readlane_b32 s7, v254, 3
	s_lshl_b32 s4, s4, 8
	s_add_u32 s4, s6, s4
	s_addc_u32 s5, s7, 0
	v_mov_b32_e32 v0, 0
	v_mov_b32_e32 v1, 1
	v_mov_b32_e32 v2, 0
	v_mov_b32_e32 v3, 0x73904
	global_atomic_add v1, v0, v1, s[4:5] offset:1088 sc0
	global_load_dword v4, v3, s[90:91] sc1
	s_waitcnt vmcnt(0)
	v_cmp_le_u32_e32 vcc, 191, v1
	s_cbranch_vccnz .Lfb_md_7
.Lfb_spin_7:
	global_load_dword v1, v0, s[4:5] offset:1088 sc1
	v_add_u32_e32 v2, 1, v2
	s_waitcnt vmcnt(0)
	v_cmp_le_u32_e32 vcc, 192, v1
	s_cbranch_vccnz .Lfb_md_7
	v_cmp_gt_u32_e32 vcc, 0x8000, v2
	s_cbranch_vccnz .Lfb_spin_7
